# new_k/new_v f32 stores in the in-projection epilogue transposed through LDS into full 256-byte rows (these context K/V tiles gate the early middle items)
# speedup vs baseline: 1.2414x; 1.0186x over previous
.LBB0_200:
	s_or_b64 exec, exec, s[52:53]
	v_mbcnt_lo_u32_b32 v204, -1, 0
	v_mbcnt_hi_u32_b32 v204, -1, v204
	s_lshr_b32 s101, s3, 6
	s_mulk_i32 s101, 0xa00
	s_add_i32 s101, s101, 0x8000
	v_and_b32_e32 v205, 15, v204
	v_lshrrev_b32_e32 v206, 4, v204
	v_lshrrev_b32_e32 v207, 3, v204
	v_and_b32_e32 v208, 7, v204
	v_mul_u32_u24_e32 v200, 0x90, v205
	v_lshl_add_u32 v200, v206, 3, v200
	v_add_u32_e32 v200, s101, v200
	v_mul_u32_u24_e32 v201, 0x90, v207
	v_lshl_add_u32 v201, v208, 4, v201
	v_add_u32_e32 v201, s101, v201
	v_sub_u32_e32 v202, v207, v205
	v_mul_i32_i24_e32 v202, 0x1200, v202
	v_lshl_add_u32 v202, v208, 4, v202
	v_lshlrev_b32_e32 v206, 3, v206
	v_sub_u32_e32 v202, v202, v206
	v_ashrrev_i32_e32 v203, 31, v202
	s_mov_b64 s[100:101], 0x9000
	v_mbcnt_lo_u32_b32 v218, -1, 0
	v_mbcnt_hi_u32_b32 v218, -1, v218
	v_and_b32_e32 v219, 15, v218
	v_lshrrev_b32_e32 v220, 4, v218
	s_lshr_b32 s97, s3, 6
	s_mul_i32 s98, s97, 0x1100
	s_add_i32 s98, s98, 0x18000
	s_cmp_eq_u32 s97, 7
	s_cselect_b32 s98, 0xd000, s98
	v_mul_u32_u24_e32 v216, 0x110, v219
	v_lshl_add_u32 v216, v220, 4, v216
	v_add_u32_e32 v216, s98, v216
	v_mul_u32_u24_e32 v217, 0x110, v220
	v_lshl_add_u32 v217, v219, 4, v217
	v_add_u32_e32 v217, s98, v217
	v_sub_u32_e32 v236, v220, v219
	v_mul_i32_i24_e32 v236, 0x1f0, v236
	v_ashrrev_i32_e32 v237, 31, v236
	v_add_u32_e32 v238, 0x1000, v236
	v_ashrrev_i32_e32 v239, 31, v238
	v_mbcnt_lo_u32_b32 v32, -1, 0
	v_mbcnt_hi_u32_b32 v32, -1, v32
	s_cmpk_gt_i32 s12, 0xfff
	v_add_u32_e32 v33, s3, v32
	v_and_b32_e32 v40, 15, v32
	v_bfe_u32 v148, v32, 4, 2
	v_lshrrev_b32_e32 v32, 1, v33
	v_and_b32_e32 v41, 0x60, v32
	v_ashrrev_i32_e32 v149, 2, v33
	v_or_b32_e32 v167, v41, v40
	v_and_b32_e32 v158, 0xffffffc0, v149
	v_lshlrev_b32_e32 v32, 4, v148
	v_or_b32_e32 v150, s12, v167
	v_lshl_or_b32 v32, v158, 2, v32
	v_lshl_or_b32 v33, v167, 2, v248
	v_add_u32_e32 v155, 0x21000, v32
	v_lshrrev_b32_e32 v36, 6, v150
	ds_read_b32 v160, v33
	v_and_b32_e32 v151, 29, v36
	s_waitcnt vmcnt(0)
	ds_read_b128 v[36:39], v155 offset:64
	ds_read_b128 v[32:35], v155
	v_bitop3_b32 v153, v41, 47, v40 bitop3:0xc8
	v_add_u32_e32 v152, s88, v158
	s_cselect_b64 s[52:53], -1, 0
	v_lshl_or_b32 v166, v148, 5, v241
	s_waitcnt lgkmcnt(0)
	v_pk_fma_f32 v[60:61], v[46:47], v[160:161], v[32:33] op_sel_hi:[1,0,1]
	ds_read_b128 v[40:43], v155 offset:128
	ds_read_b128 v[44:47], v155 offset:192
	v_cmp_gt_i32_e32 vcc, s18, v152
	v_pk_fma_f32 v[52:53], v[52:53], v[160:161], v[36:37] op_sel_hi:[1,0,1]
	v_pk_fma_f32 v[62:63], v[48:49], v[160:161], v[34:35] op_sel_hi:[1,0,1]
	v_pk_fma_f32 v[54:55], v[54:55], v[160:161], v[38:39] op_sel_hi:[1,0,1]
	s_waitcnt lgkmcnt(1)
	v_pk_fma_f32 v[56:57], v[56:57], v[160:161], v[40:41] op_sel_hi:[1,0,1]
	s_waitcnt lgkmcnt(0)
	v_pk_fma_f32 v[48:49], v[144:145], v[160:161], v[44:45] op_sel_hi:[1,0,1]
	v_pk_fma_f32 v[58:59], v[58:59], v[160:161], v[42:43] op_sel_hi:[1,0,1]
	v_pk_fma_f32 v[50:51], v[146:147], v[160:161], v[46:47] op_sel_hi:[1,0,1]
	s_and_b64 s[90:91], s[52:53], vcc
	v_lshl_add_u32 v159, v151, 7, v166
	v_lshl_add_u32 v169, v153, 7, v166
	s_and_saveexec_b64 s[54:55], s[90:91]
	s_cbranch_execz .LBB0_202
	ds_read_b128 v[144:147], v159
	ds_read_b128 v[162:165], v159 offset:16
	s_waitcnt lgkmcnt(1)
	v_mov_b32_e32 v157, v146
	v_mov_b32_e32 v146, v145
	v_mov_b32_e32 v156, v144
	v_pk_mul_f32 v[144:145], v[52:53], v[146:147]
	s_nop 0
	v_pk_fma_f32 v[170:171], v[60:61], v[156:157], v[144:145] neg_lo:[0,0,1] neg_hi:[0,0,1]
	v_pk_mul_f32 v[60:61], v[60:61], v[146:147]
	s_nop 0
	v_pk_fma_f32 v[52:53], v[52:53], v[156:157], v[60:61]
	s_waitcnt lgkmcnt(0)
	v_mov_b32_e32 v61, v164
	v_mov_b32_e32 v164, v163
	v_mov_b32_e32 v60, v162
	v_pk_mul_f32 v[144:145], v[54:55], v[164:165]
	s_nop 0
	v_pk_fma_f32 v[156:157], v[62:63], v[60:61], v[144:145] neg_lo:[0,0,1] neg_hi:[0,0,1]
	v_pk_mul_f32 v[62:63], v[62:63], v[164:165]
	s_nop 0
	v_pk_fma_f32 v[54:55], v[54:55], v[60:61], v[62:63]
	ds_read_b128 v[60:63], v169
	ds_read_b128 v[144:147], v169 offset:16
	s_waitcnt lgkmcnt(1)
	v_mov_b32_e32 v163, v62
	v_mov_b32_e32 v62, v61
	v_mov_b32_e32 v162, v60
	v_pk_mul_f32 v[60:61], v[48:49], v[62:63]
	s_nop 0
	v_pk_fma_f32 v[164:165], v[56:57], v[162:163], v[60:61] neg_lo:[0,0,1] neg_hi:[0,0,1]
	v_pk_mul_f32 v[56:57], v[56:57], v[62:63]
	v_mov_b64_e32 v[62:63], v[156:157]
	v_pk_fma_f32 v[48:49], v[48:49], v[162:163], v[56:57]
	s_waitcnt lgkmcnt(0)
	v_mov_b32_e32 v57, v146
	v_mov_b32_e32 v146, v145
	v_mov_b32_e32 v56, v144
	v_pk_mul_f32 v[60:61], v[50:51], v[146:147]
	s_nop 0
	v_pk_fma_f32 v[144:145], v[58:59], v[56:57], v[60:61] neg_lo:[0,0,1] neg_hi:[0,0,1]
	v_pk_mul_f32 v[58:59], v[58:59], v[146:147]
	v_mov_b64_e32 v[60:61], v[170:171]
	v_pk_fma_f32 v[50:51], v[50:51], v[56:57], v[58:59]
	v_mov_b64_e32 v[56:57], v[164:165]
	v_mov_b64_e32 v[58:59], v[144:145]
.LBB0_202:
	s_or_b64 exec, exec, s[54:55]
	s_lshr_b32 s13, s12, 6
	s_or_b32 s13, s13, s86
	v_lshlrev_b32_e32 v198, 3, v148
	s_lshl_b32 s23, s13, 8
	v_cmp_gt_i32_e32 vcc, s22, v152
	v_lshl_add_u64 v[156:157], s[6:7], 0, v[198:199]
	v_or_b32_e32 v144, s23, v167
	v_cndmask_b32_e32 v154, 1.0, v249, vcc
	v_lshlrev_b32_e32 v151, 2, v148
	v_and_b32_e32 v161, 64, v149
	v_mad_i64_i32 v[164:165], s[54:55], v150, s62, v[156:157]
	v_ashrrev_i32_e32 v145, 31, v144
	v_ashrrev_i32_e32 v153, 31, v152
	v_pk_mul_f32 v[146:147], v[154:155], v[60:61] op_sel_hi:[0,1]
	v_pk_mul_f32 v[148:149], v[154:155], v[62:63] op_sel_hi:[0,1]
	v_lshlrev_b64 v[162:163], 9, v[144:145]
	v_lshl_add_u64 v[144:145], v[152:153], 1, v[164:165]
	v_cvt_pk_bf16_f32 v146, v146, v147
	v_cvt_pk_bf16_f32 v147, v148, v149
	ds_write_b64 v200, v[146:147]
	v_pk_mul_f32 v[146:147], v[154:155], v[52:53] op_sel_hi:[0,1]
	v_pk_mul_f32 v[148:149], v[154:155], v[54:55] op_sel_hi:[0,1]
	v_cvt_pk_bf16_f32 v146, v146, v147
	v_cvt_pk_bf16_f32 v147, v148, v149
	ds_write_b64 v200, v[146:147] offset:32
	v_pk_mul_f32 v[146:147], v[154:155], v[56:57] op_sel_hi:[0,1]
	v_pk_mul_f32 v[148:149], v[154:155], v[58:59] op_sel_hi:[0,1]
	v_cvt_pk_bf16_f32 v146, v146, v147
	v_cvt_pk_bf16_f32 v147, v148, v149
	ds_write_b64 v200, v[146:147] offset:64
	v_pk_mul_f32 v[146:147], v[154:155], v[48:49] op_sel_hi:[0,1]
	v_pk_mul_f32 v[148:149], v[154:155], v[50:51] op_sel_hi:[0,1]
	v_cvt_pk_bf16_f32 v146, v146, v147
	v_cvt_pk_bf16_f32 v147, v148, v149
	ds_write_b64 v200, v[146:147] offset:96
	s_waitcnt lgkmcnt(0)
	ds_read_b128 v[204:207], v201
	ds_read_b128 v[208:211], v201 offset:1152
	v_lshl_add_u64 v[212:213], v[144:145], 0, v[202:203]
	v_lshl_add_u64 v[214:215], v[212:213], 0, s[100:101]
	s_waitcnt lgkmcnt(0)
	global_store_dwordx4 v[212:213], v[204:207], off sc1
	global_store_dwordx4 v[214:215], v[208:211], off sc1
	v_and_b32_e32 v144, 0xffffff00, v152
	v_cmp_eq_u32_e32 vcc, s22, v144
	s_xor_b64 s[54:55], s[52:53], -1
	s_and_b64 s[92:93], s[54:55], vcc
	v_and_b32_e32 v168, 0x280, v152
	v_lshlrev_b32_e32 v150, 2, v161
	v_lshlrev_b32_e32 v148, 2, v151
	s_and_saveexec_b64 s[94:95], s[92:93]
	s_cbranch_execz .LBB0_204
	v_cmp_eq_u32_e32 vcc, s18, v168
	v_mov_b32_e32 v151, v199
	v_mov_b32_e32 v149, v199
	v_cndmask_b32_e32 v198, 0, v250, vcc
	v_lshl_add_u64 v[144:145], s[34:35], 0, v[198:199]
	v_lshl_add_u64 v[144:145], v[144:145], 0, v[162:163]
	v_lshl_add_u64 v[144:145], v[144:145], 0, v[150:151]
	v_lshl_add_u64 v[144:145], v[144:145], 0, v[148:149]
	ds_write_b128 v216, v[60:63]
	ds_write_b128 v216, v[52:55] offset:64
	ds_write_b128 v216, v[56:59] offset:128
	ds_write_b128 v216, v[48:51] offset:192
	ds_read_b128 v[220:223], v217
	ds_read_b128 v[224:227], v217 offset:1088
	ds_read_b128 v[228:231], v217 offset:2176
	ds_read_b128 v[232:235], v217 offset:3264
	v_lshl_add_u64 v[242:243], v[144:145], 0, v[238:239]
	v_lshl_add_u64 v[218:219], v[144:145], 0, v[236:237]
	s_waitcnt lgkmcnt(0)
	global_store_dwordx4 v[218:219], v[220:223], off
	global_store_dwordx4 v[218:219], v[224:227], off offset:2048
	global_store_dwordx4 v[242:243], v[228:231], off
	global_store_dwordx4 v[242:243], v[232:235], off offset:2048

.LBB0_206:
	s_or_b64 exec, exec, s[52:53]
	v_cmp_gt_i32_e32 vcc, s22, v137
	s_ashr_i32 s89, s88, 31
	v_ashrrev_i32_e32 v159, 31, v158
	v_cndmask_b32_e32 v136, 1.0, v249, vcc
	v_lshl_add_u64 v[138:139], v[158:159], 0, s[88:89]
	v_lshl_add_u64 v[158:159], v[138:139], 1, v[164:165]
	v_pk_mul_f32 v[160:161], v[136:137], v[144:145] op_sel_hi:[0,1]
	v_pk_mul_f32 v[164:165], v[136:137], v[146:147] op_sel_hi:[0,1]
	v_cvt_pk_bf16_f32 v160, v160, v161
	v_cvt_pk_bf16_f32 v161, v164, v165
	ds_write_b64 v200, v[160:161]
	v_pk_mul_f32 v[160:161], v[136:137], v[140:141] op_sel_hi:[0,1]
	v_pk_mul_f32 v[164:165], v[136:137], v[142:143] op_sel_hi:[0,1]
	v_cvt_pk_bf16_f32 v160, v160, v161
	v_cvt_pk_bf16_f32 v161, v164, v165
	ds_write_b64 v200, v[160:161] offset:32
	v_pk_mul_f32 v[160:161], v[136:137], v[132:133] op_sel_hi:[0,1]
	v_pk_mul_f32 v[164:165], v[136:137], v[134:135] op_sel_hi:[0,1]
	v_cvt_pk_bf16_f32 v160, v160, v161
	v_cvt_pk_bf16_f32 v161, v164, v165
	ds_write_b64 v200, v[160:161] offset:64
	v_pk_mul_f32 v[160:161], v[136:137], v[128:129] op_sel_hi:[0,1]
	v_pk_mul_f32 v[164:165], v[136:137], v[130:131] op_sel_hi:[0,1]
	v_and_b32_e32 v149, 0xffffff00, v137
	v_cvt_pk_bf16_f32 v160, v160, v161
	v_cvt_pk_bf16_f32 v161, v164, v165
	v_cmp_eq_u32_e32 vcc, s22, v149
	ds_write_b64 v200, v[160:161] offset:96
	s_waitcnt lgkmcnt(0)
	ds_read_b128 v[204:207], v201
	ds_read_b128 v[208:211], v201 offset:1152
	v_lshl_add_u64 v[212:213], v[158:159], 0, v[202:203]
	v_lshl_add_u64 v[214:215], v[212:213], 0, s[100:101]
	s_waitcnt lgkmcnt(0)
	global_store_dwordx4 v[212:213], v[204:207], off offset:256 sc1
	global_store_dwordx4 v[214:215], v[208:211], off offset:256 sc1
	s_and_b64 s[88:89], s[54:55], vcc
	v_and_b32_e32 v158, 0x280, v137
	s_and_saveexec_b64 s[52:53], s[88:89]
	s_cbranch_execz .LBB0_208
	v_cmp_eq_u32_e32 vcc, s18, v158
	v_mov_b32_e32 v151, v199
	v_mov_b32_e32 v149, v199
	v_cndmask_b32_e32 v198, 0, v250, vcc
	v_lshl_add_u64 v[160:161], s[34:35], 0, v[198:199]
	v_lshl_add_u64 v[160:161], v[160:161], 0, v[162:163]
	v_lshl_add_u64 v[160:161], v[160:161], 0, v[150:151]
	v_lshl_add_u64 v[160:161], v[160:161], 0, v[148:149]
	ds_write_b128 v216, v[144:147]
	ds_write_b128 v216, v[140:143] offset:64
	ds_write_b128 v216, v[132:135] offset:128
	ds_write_b128 v216, v[128:131] offset:192
	ds_read_b128 v[220:223], v217
	ds_read_b128 v[224:227], v217 offset:1088
	ds_read_b128 v[228:231], v217 offset:2176
	ds_read_b128 v[232:235], v217 offset:3264
	v_lshl_add_u64 v[242:243], v[160:161], 0, v[238:239]
	v_lshl_add_u64 v[218:219], v[160:161], 0, v[236:237]
	s_waitcnt lgkmcnt(0)
	global_store_dwordx4 v[218:219], v[220:223], off
	global_store_dwordx4 v[218:219], v[224:227], off offset:2048
	global_store_dwordx4 v[242:243], v[228:231], off
	global_store_dwordx4 v[242:243], v[232:235], off offset:2048

.LBB0_210:
	s_or_b64 exec, exec, s[52:53]
	v_mov_b32_e32 v155, v154
	v_mad_i64_i32 v[126:127], s[52:53], v137, s62, v[156:157]
	v_pk_mul_f32 v[142:143], v[154:155], v[128:129]
	v_pk_mul_f32 v[144:145], v[154:155], v[130:131]
	v_lshl_add_u64 v[140:141], v[152:153], 1, v[126:127]
	v_cvt_pk_bf16_f32 v142, v142, v143
	v_cvt_pk_bf16_f32 v143, v144, v145
	ds_write_b64 v200, v[142:143]
	v_pk_mul_f32 v[142:143], v[154:155], v[120:121]
	v_pk_mul_f32 v[144:145], v[154:155], v[122:123]
	v_cvt_pk_bf16_f32 v142, v142, v143
	v_cvt_pk_bf16_f32 v143, v144, v145
	ds_write_b64 v200, v[142:143] offset:32
	v_pk_mul_f32 v[142:143], v[154:155], v[116:117]
	v_pk_mul_f32 v[144:145], v[154:155], v[118:119]
	v_or_b32_e32 v124, s23, v133
	v_cvt_pk_bf16_f32 v142, v142, v143
	v_cvt_pk_bf16_f32 v143, v144, v145
	v_ashrrev_i32_e32 v125, 31, v124
	ds_write_b64 v200, v[142:143] offset:64
	v_pk_mul_f32 v[142:143], v[154:155], v[112:113]
	v_pk_mul_f32 v[144:145], v[154:155], v[114:115]
	v_lshlrev_b64 v[124:125], 9, v[124:125]
	v_cvt_pk_bf16_f32 v142, v142, v143
	v_cvt_pk_bf16_f32 v143, v144, v145
	ds_write_b64 v200, v[142:143] offset:96
	s_waitcnt lgkmcnt(0)
	ds_read_b128 v[204:207], v201
	ds_read_b128 v[208:211], v201 offset:1152
	v_lshl_add_u64 v[212:213], v[140:141], 0, v[202:203]
	v_lshl_add_u64 v[214:215], v[212:213], 0, s[100:101]
	s_waitcnt lgkmcnt(0)
	global_store_dwordx4 v[212:213], v[204:207], off sc1
	global_store_dwordx4 v[214:215], v[208:211], off sc1
	s_and_saveexec_b64 s[52:53], s[92:93]
	s_cbranch_execz .LBB0_212
	v_cmp_eq_u32_e32 vcc, s18, v168
	v_mov_b32_e32 v151, v199
	v_mov_b32_e32 v149, v199
	v_cndmask_b32_e32 v198, 0, v250, vcc
	v_lshl_add_u64 v[140:141], s[34:35], 0, v[198:199]
	v_lshl_add_u64 v[140:141], v[140:141], 0, v[124:125]
	v_lshl_add_u64 v[140:141], v[140:141], 0, v[150:151]
	v_lshl_add_u64 v[140:141], v[140:141], 0, v[148:149]
	ds_write_b128 v216, v[128:131]
	ds_write_b128 v216, v[120:123] offset:64
	ds_write_b128 v216, v[116:119] offset:128
	ds_write_b128 v216, v[112:115] offset:192
	ds_read_b128 v[220:223], v217
	ds_read_b128 v[224:227], v217 offset:1088
	ds_read_b128 v[228:231], v217 offset:2176
	ds_read_b128 v[232:235], v217 offset:3264
	v_lshl_add_u64 v[242:243], v[140:141], 0, v[238:239]
	v_lshl_add_u64 v[218:219], v[140:141], 0, v[236:237]
	s_waitcnt lgkmcnt(0)
	global_store_dwordx4 v[218:219], v[220:223], off
	global_store_dwordx4 v[218:219], v[224:227], off offset:2048
	global_store_dwordx4 v[242:243], v[228:231], off
	global_store_dwordx4 v[242:243], v[232:235], off offset:2048

.LBB0_214:
	s_or_b64 exec, exec, s[52:53]
	v_mov_b32_e32 v137, v136
	v_pk_mul_f32 v[110:111], v[136:137], v[112:113]
	v_pk_mul_f32 v[116:117], v[136:137], v[114:115]
	v_lshl_add_u64 v[108:109], v[138:139], 1, v[126:127]
	v_cvt_pk_bf16_f32 v110, v110, v111
	v_cvt_pk_bf16_f32 v111, v116, v117
	ds_write_b64 v200, v[110:111]
	v_pk_mul_f32 v[110:111], v[136:137], v[104:105]
	v_pk_mul_f32 v[116:117], v[136:137], v[106:107]
	v_cvt_pk_bf16_f32 v110, v110, v111
	v_cvt_pk_bf16_f32 v111, v116, v117
	ds_write_b64 v200, v[110:111] offset:32
	v_pk_mul_f32 v[110:111], v[136:137], v[100:101]
	v_pk_mul_f32 v[116:117], v[136:137], v[102:103]
	v_cvt_pk_bf16_f32 v110, v110, v111
	v_cvt_pk_bf16_f32 v111, v116, v117
	ds_write_b64 v200, v[110:111] offset:64
	v_pk_mul_f32 v[110:111], v[136:137], v[96:97]
	v_pk_mul_f32 v[116:117], v[136:137], v[98:99]
	v_cvt_pk_bf16_f32 v110, v110, v111
	v_cvt_pk_bf16_f32 v111, v116, v117
	ds_write_b64 v200, v[110:111] offset:96
	s_waitcnt lgkmcnt(0)
	ds_read_b128 v[204:207], v201
	ds_read_b128 v[208:211], v201 offset:1152
	v_lshl_add_u64 v[212:213], v[108:109], 0, v[202:203]
	v_lshl_add_u64 v[214:215], v[212:213], 0, s[100:101]
	s_waitcnt lgkmcnt(0)
	global_store_dwordx4 v[212:213], v[204:207], off offset:256 sc1
	global_store_dwordx4 v[214:215], v[208:211], off offset:256 sc1
	s_and_saveexec_b64 s[52:53], s[88:89]
	s_cbranch_execz .LBB0_216
	v_cmp_eq_u32_e32 vcc, s18, v158
	v_mov_b32_e32 v151, v199
	v_mov_b32_e32 v149, v199
	v_cndmask_b32_e32 v198, 0, v250, vcc
	v_lshl_add_u64 v[108:109], s[34:35], 0, v[198:199]
	v_lshl_add_u64 v[108:109], v[108:109], 0, v[124:125]
	v_lshl_add_u64 v[108:109], v[108:109], 0, v[150:151]
	v_lshl_add_u64 v[108:109], v[108:109], 0, v[148:149]
	ds_write_b128 v216, v[112:115]
	ds_write_b128 v216, v[104:107] offset:64
	ds_write_b128 v216, v[100:103] offset:128
	ds_write_b128 v216, v[96:99] offset:192
	ds_read_b128 v[220:223], v217
	ds_read_b128 v[224:227], v217 offset:1088
	ds_read_b128 v[228:231], v217 offset:2176
	ds_read_b128 v[232:235], v217 offset:3264
	v_lshl_add_u64 v[242:243], v[108:109], 0, v[238:239]
	v_lshl_add_u64 v[218:219], v[108:109], 0, v[236:237]
	s_waitcnt lgkmcnt(0)
	global_store_dwordx4 v[218:219], v[220:223], off
	global_store_dwordx4 v[218:219], v[224:227], off offset:2048
	global_store_dwordx4 v[242:243], v[228:231], off
	global_store_dwordx4 v[242:243], v[232:235], off offset:2048

.LBB0_218:
	s_or_b64 exec, exec, s[52:53]
	v_mad_i64_i32 v[94:95], s[52:53], v103, s62, v[156:157]
	v_pk_mul_f32 v[106:107], v[154:155], v[96:97]
	v_pk_mul_f32 v[108:109], v[154:155], v[98:99]
	v_lshl_add_u64 v[104:105], v[152:153], 1, v[94:95]
	v_cvt_pk_bf16_f32 v106, v106, v107
	v_cvt_pk_bf16_f32 v107, v108, v109
	ds_write_b64 v200, v[106:107]
	v_pk_mul_f32 v[106:107], v[154:155], v[88:89]
	v_pk_mul_f32 v[108:109], v[154:155], v[90:91]
	v_cvt_pk_bf16_f32 v106, v106, v107
	v_cvt_pk_bf16_f32 v107, v108, v109
	ds_write_b64 v200, v[106:107] offset:32
	v_pk_mul_f32 v[106:107], v[154:155], v[84:85]
	v_pk_mul_f32 v[108:109], v[154:155], v[86:87]
	v_or_b32_e32 v92, s23, v101
	v_cvt_pk_bf16_f32 v106, v106, v107
	v_cvt_pk_bf16_f32 v107, v108, v109
	v_ashrrev_i32_e32 v93, 31, v92
	ds_write_b64 v200, v[106:107] offset:64
	v_pk_mul_f32 v[106:107], v[154:155], v[80:81]
	v_pk_mul_f32 v[108:109], v[154:155], v[82:83]
	v_lshlrev_b64 v[92:93], 9, v[92:93]
	v_cvt_pk_bf16_f32 v106, v106, v107
	v_cvt_pk_bf16_f32 v107, v108, v109
	ds_write_b64 v200, v[106:107] offset:96
	s_waitcnt lgkmcnt(0)
	ds_read_b128 v[204:207], v201
	ds_read_b128 v[208:211], v201 offset:1152
	v_lshl_add_u64 v[212:213], v[104:105], 0, v[202:203]
	v_lshl_add_u64 v[214:215], v[212:213], 0, s[100:101]
	s_waitcnt lgkmcnt(0)
	global_store_dwordx4 v[212:213], v[204:207], off sc1
	global_store_dwordx4 v[214:215], v[208:211], off sc1
	s_and_saveexec_b64 s[52:53], s[92:93]
	s_cbranch_execz .LBB0_220
	v_cmp_eq_u32_e32 vcc, s18, v168
	v_mov_b32_e32 v151, v199
	v_mov_b32_e32 v149, v199
	v_cndmask_b32_e32 v198, 0, v250, vcc
	v_lshl_add_u64 v[104:105], s[34:35], 0, v[198:199]
	v_lshl_add_u64 v[104:105], v[104:105], 0, v[92:93]
	v_lshl_add_u64 v[104:105], v[104:105], 0, v[150:151]
	v_lshl_add_u64 v[104:105], v[104:105], 0, v[148:149]
	ds_write_b128 v216, v[96:99]
	ds_write_b128 v216, v[88:91] offset:64
	ds_write_b128 v216, v[84:87] offset:128
	ds_write_b128 v216, v[80:83] offset:192
	ds_read_b128 v[220:223], v217
	ds_read_b128 v[224:227], v217 offset:1088
	ds_read_b128 v[228:231], v217 offset:2176
	ds_read_b128 v[232:235], v217 offset:3264
	v_lshl_add_u64 v[242:243], v[104:105], 0, v[238:239]
	v_lshl_add_u64 v[218:219], v[104:105], 0, v[236:237]
	s_waitcnt lgkmcnt(0)
	global_store_dwordx4 v[218:219], v[220:223], off
	global_store_dwordx4 v[218:219], v[224:227], off offset:2048
	global_store_dwordx4 v[242:243], v[228:231], off
	global_store_dwordx4 v[242:243], v[232:235], off offset:2048

.LBB0_222:
	s_or_b64 exec, exec, s[52:53]
	v_pk_mul_f32 v[78:79], v[136:137], v[80:81]
	v_pk_mul_f32 v[84:85], v[136:137], v[82:83]
	v_lshl_add_u64 v[76:77], v[138:139], 1, v[94:95]
	v_cvt_pk_bf16_f32 v78, v78, v79
	v_cvt_pk_bf16_f32 v79, v84, v85
	ds_write_b64 v200, v[78:79]
	v_pk_mul_f32 v[78:79], v[136:137], v[72:73]
	v_pk_mul_f32 v[84:85], v[136:137], v[74:75]
	v_cvt_pk_bf16_f32 v78, v78, v79
	v_cvt_pk_bf16_f32 v79, v84, v85
	ds_write_b64 v200, v[78:79] offset:32
	v_pk_mul_f32 v[78:79], v[136:137], v[68:69]
	v_pk_mul_f32 v[84:85], v[136:137], v[70:71]
	v_cvt_pk_bf16_f32 v78, v78, v79
	v_cvt_pk_bf16_f32 v79, v84, v85
	ds_write_b64 v200, v[78:79] offset:64
	v_pk_mul_f32 v[78:79], v[136:137], v[64:65]
	v_pk_mul_f32 v[84:85], v[136:137], v[66:67]
	v_cvt_pk_bf16_f32 v78, v78, v79
	v_cvt_pk_bf16_f32 v79, v84, v85
	ds_write_b64 v200, v[78:79] offset:96
	s_waitcnt lgkmcnt(0)
	ds_read_b128 v[204:207], v201
	ds_read_b128 v[208:211], v201 offset:1152
	v_lshl_add_u64 v[212:213], v[76:77], 0, v[202:203]
	v_lshl_add_u64 v[214:215], v[212:213], 0, s[100:101]
	s_waitcnt lgkmcnt(0)
	global_store_dwordx4 v[212:213], v[204:207], off offset:256 sc1
	global_store_dwordx4 v[214:215], v[208:211], off offset:256 sc1
	s_and_saveexec_b64 s[52:53], s[88:89]
	s_cbranch_execz .LBB0_224
	v_cmp_eq_u32_e32 vcc, s18, v158
	v_mov_b32_e32 v151, v199
	v_mov_b32_e32 v149, v199
	v_cndmask_b32_e32 v198, 0, v250, vcc
	v_lshl_add_u64 v[76:77], s[34:35], 0, v[198:199]
	v_lshl_add_u64 v[76:77], v[76:77], 0, v[92:93]
	v_lshl_add_u64 v[76:77], v[76:77], 0, v[150:151]
	v_lshl_add_u64 v[76:77], v[76:77], 0, v[148:149]
	ds_write_b128 v216, v[80:83]
	ds_write_b128 v216, v[72:75] offset:64
	ds_write_b128 v216, v[68:71] offset:128
	ds_write_b128 v216, v[64:67] offset:192
	ds_read_b128 v[220:223], v217
	ds_read_b128 v[224:227], v217 offset:1088
	ds_read_b128 v[228:231], v217 offset:2176
	ds_read_b128 v[232:235], v217 offset:3264
	v_lshl_add_u64 v[242:243], v[76:77], 0, v[238:239]
	v_lshl_add_u64 v[218:219], v[76:77], 0, v[236:237]
	s_waitcnt lgkmcnt(0)
	global_store_dwordx4 v[218:219], v[220:223], off
	global_store_dwordx4 v[218:219], v[224:227], off offset:2048
	global_store_dwordx4 v[242:243], v[228:231], off
	global_store_dwordx4 v[242:243], v[232:235], off offset:2048

.LBB0_226:
	s_or_b64 exec, exec, s[12:13]
	v_mad_i64_i32 v[30:31], s[12:13], v66, s62, v[156:157]
	v_pk_mul_f32 v[40:41], v[154:155], v[32:33]
	v_pk_mul_f32 v[42:43], v[154:155], v[34:35]
	v_lshl_add_u64 v[38:39], v[152:153], 1, v[30:31]
	v_cvt_pk_bf16_f32 v40, v40, v41
	v_cvt_pk_bf16_f32 v41, v42, v43
	ds_write_b64 v200, v[40:41]
	v_pk_mul_f32 v[40:41], v[154:155], v[24:25]
	v_pk_mul_f32 v[42:43], v[154:155], v[26:27]
	v_cvt_pk_bf16_f32 v40, v40, v41
	v_cvt_pk_bf16_f32 v41, v42, v43
	ds_write_b64 v200, v[40:41] offset:32
	v_pk_mul_f32 v[40:41], v[154:155], v[20:21]
	v_pk_mul_f32 v[42:43], v[154:155], v[22:23]
	v_or_b32_e32 v28, s23, v65
	v_cvt_pk_bf16_f32 v40, v40, v41
	v_cvt_pk_bf16_f32 v41, v42, v43
	v_ashrrev_i32_e32 v29, 31, v28
	ds_write_b64 v200, v[40:41] offset:64
	v_pk_mul_f32 v[40:41], v[154:155], v[16:17]
	v_pk_mul_f32 v[42:43], v[154:155], v[18:19]
	v_lshlrev_b64 v[28:29], 9, v[28:29]
	v_cvt_pk_bf16_f32 v40, v40, v41
	v_cvt_pk_bf16_f32 v41, v42, v43
	ds_write_b64 v200, v[40:41] offset:96
	s_waitcnt lgkmcnt(0)
	ds_read_b128 v[204:207], v201
	ds_read_b128 v[208:211], v201 offset:1152
	v_lshl_add_u64 v[212:213], v[38:39], 0, v[202:203]
	v_lshl_add_u64 v[214:215], v[212:213], 0, s[100:101]
	s_waitcnt lgkmcnt(0)
	global_store_dwordx4 v[212:213], v[204:207], off sc1
	global_store_dwordx4 v[214:215], v[208:211], off sc1
	s_and_saveexec_b64 s[12:13], s[92:93]
	s_cbranch_execz .LBB0_228
	v_cmp_eq_u32_e32 vcc, s18, v168
	v_mov_b32_e32 v151, v199
	v_mov_b32_e32 v149, v199
	v_cndmask_b32_e32 v198, 0, v250, vcc
	v_lshl_add_u64 v[38:39], s[34:35], 0, v[198:199]
	v_lshl_add_u64 v[38:39], v[38:39], 0, v[28:29]
	v_lshl_add_u64 v[38:39], v[38:39], 0, v[150:151]
	v_lshl_add_u64 v[38:39], v[38:39], 0, v[148:149]
	ds_write_b128 v216, v[32:35]
	ds_write_b128 v216, v[24:27] offset:64
	ds_write_b128 v216, v[20:23] offset:128
	ds_write_b128 v216, v[16:19] offset:192
	ds_read_b128 v[220:223], v217
	ds_read_b128 v[224:227], v217 offset:1088
	ds_read_b128 v[228:231], v217 offset:2176
	ds_read_b128 v[232:235], v217 offset:3264
	v_lshl_add_u64 v[242:243], v[38:39], 0, v[238:239]
	v_lshl_add_u64 v[218:219], v[38:39], 0, v[236:237]
	s_waitcnt lgkmcnt(0)
	global_store_dwordx4 v[218:219], v[220:223], off
	global_store_dwordx4 v[218:219], v[224:227], off offset:2048
	global_store_dwordx4 v[242:243], v[228:231], off
	global_store_dwordx4 v[242:243], v[232:235], off offset:2048

.LBB0_230:
	s_or_b64 exec, exec, s[12:13]
	v_pk_mul_f32 v[14:15], v[136:137], v[16:17]
	v_pk_mul_f32 v[20:21], v[136:137], v[18:19]
	v_lshl_add_u64 v[12:13], v[138:139], 1, v[30:31]
	v_cvt_pk_bf16_f32 v14, v14, v15
	v_cvt_pk_bf16_f32 v15, v20, v21
	ds_write_b64 v200, v[14:15]
	v_pk_mul_f32 v[14:15], v[136:137], v[8:9]
	v_pk_mul_f32 v[20:21], v[136:137], v[10:11]
	v_cvt_pk_bf16_f32 v14, v14, v15
	v_cvt_pk_bf16_f32 v15, v20, v21
	ds_write_b64 v200, v[14:15] offset:32
	v_pk_mul_f32 v[14:15], v[136:137], v[4:5]
	v_pk_mul_f32 v[20:21], v[136:137], v[6:7]
	v_cvt_pk_bf16_f32 v14, v14, v15
	v_cvt_pk_bf16_f32 v15, v20, v21
	ds_write_b64 v200, v[14:15] offset:64
	v_pk_mul_f32 v[14:15], v[136:137], v[0:1]
	v_pk_mul_f32 v[20:21], v[136:137], v[2:3]
	v_cvt_pk_bf16_f32 v14, v14, v15
	v_cvt_pk_bf16_f32 v15, v20, v21
	ds_write_b64 v200, v[14:15] offset:96
	s_waitcnt lgkmcnt(0)
	ds_read_b128 v[204:207], v201
	ds_read_b128 v[208:211], v201 offset:1152
	v_lshl_add_u64 v[212:213], v[12:13], 0, v[202:203]
	v_lshl_add_u64 v[214:215], v[212:213], 0, s[100:101]
	s_waitcnt lgkmcnt(0)
	global_store_dwordx4 v[212:213], v[204:207], off offset:256 sc1
	global_store_dwordx4 v[214:215], v[208:211], off offset:256 sc1
	s_and_saveexec_b64 s[12:13], s[88:89]
	s_cbranch_execz .LBB0_189
	v_cmp_eq_u32_e32 vcc, s18, v158
	v_mov_b32_e32 v151, v199
	v_mov_b32_e32 v149, v199
	v_cndmask_b32_e32 v198, 0, v250, vcc
	v_lshl_add_u64 v[12:13], s[34:35], 0, v[198:199]
	v_lshl_add_u64 v[12:13], v[12:13], 0, v[28:29]
	v_lshl_add_u64 v[12:13], v[12:13], 0, v[150:151]
	v_lshl_add_u64 v[12:13], v[12:13], 0, v[148:149]
	ds_write_b128 v216, v[16:19]
	ds_write_b128 v216, v[8:11] offset:64
	ds_write_b128 v216, v[4:7] offset:128
	ds_write_b128 v216, v[0:3] offset:192
	ds_read_b128 v[220:223], v217
	ds_read_b128 v[224:227], v217 offset:1088
	ds_read_b128 v[228:231], v217 offset:2176
	ds_read_b128 v[232:235], v217 offset:3264
	v_lshl_add_u64 v[242:243], v[12:13], 0, v[238:239]
	v_lshl_add_u64 v[218:219], v[12:13], 0, v[236:237]
	s_waitcnt lgkmcnt(0)
	global_store_dwordx4 v[218:219], v[220:223], off
	global_store_dwordx4 v[218:219], v[224:227], off offset:2048
	global_store_dwordx4 v[242:243], v[228:231], off
	global_store_dwordx4 v[242:243], v[232:235], off offset:2048
	s_branch .LBB0_189
